# GEMM tile boundary: removed the compiler-inserted full vmcnt drain before the next tile's K-loop (epilogue stores overlap the first phases)
# speedup vs baseline: 1.0047x; 1.0012x over previous
; template <class Epi, class Sched, bool STAMP = false>
; __device__ __forceinline__ void gemm_phase(PG8_LAS unsigned char* lds, const Gemm g, const Sched& S, const Epi& E, unsigned long long* stamps) {
;     ...
; #pragma unroll
;         for (int a = 0; a < 2; ++a)
; #pragma unroll
;             for (int b = 0; b < 2; ++b)
; #pragma unroll
;                 for (int m = 0; m < 4; ++m)
; #pragma unroll
;                     for (int n = 0; n < 2; ++n) acc[a][b][m][n] = (f32x4){0.f, 0.f, 0.f, 0.f};
;         cur = nxt; cA = nA; cB = nB; ++ui;
.LBB0_744:
	s_add_u32 s0, s22, 0x80
	s_addc_u32 s1, s23, 0
	s_add_u32 s88, s88, 0x100
	v_mov_b32_e32 v2, 0
	s_addc_u32 s89, s89, 0
	s_mov_b32 s22, 0
	v_mov_b32_e32 v3, v2
	v_mov_b32_e32 v4, v2
	v_mov_b32_e32 v5, v2
	v_mov_b32_e32 v6, v2
	v_mov_b32_e32 v7, v2
	v_mov_b32_e32 v8, v2
	v_mov_b32_e32 v9, v2
	v_mov_b32_e32 v10, v2
	v_mov_b32_e32 v11, v2
	v_mov_b32_e32 v12, v2
	v_mov_b32_e32 v13, v2
	v_mov_b32_e32 v14, v2
	v_mov_b32_e32 v15, v2
	v_mov_b32_e32 v16, v2
	v_mov_b32_e32 v17, v2
	v_mov_b32_e32 v26, v2
	v_mov_b32_e32 v27, v2
	v_mov_b32_e32 v28, v2
	v_mov_b32_e32 v29, v2
	v_mov_b32_e32 v30, v2
	v_mov_b32_e32 v31, v2
	v_mov_b32_e32 v32, v2
	v_mov_b32_e32 v33, v2
	v_mov_b32_e32 v42, v2
	v_mov_b32_e32 v43, v2
	v_mov_b32_e32 v44, v2
	v_mov_b32_e32 v45, v2
	v_mov_b32_e32 v46, v2
	v_mov_b32_e32 v47, v2
	v_mov_b32_e32 v48, v2
	v_mov_b32_e32 v49, v2
	v_mov_b32_e32 v18, v2
	v_mov_b32_e32 v19, v2
	v_mov_b32_e32 v20, v2
	v_mov_b32_e32 v21, v2
	v_mov_b32_e32 v22, v2
	v_mov_b32_e32 v23, v2
	v_mov_b32_e32 v24, v2
	v_mov_b32_e32 v25, v2
	v_mov_b32_e32 v34, v2
	v_mov_b32_e32 v35, v2
	v_mov_b32_e32 v36, v2
	v_mov_b32_e32 v37, v2
	v_mov_b32_e32 v38, v2
	v_mov_b32_e32 v39, v2
	v_mov_b32_e32 v40, v2
	v_mov_b32_e32 v41, v2
	v_mov_b32_e32 v50, v2
	v_mov_b32_e32 v51, v2
	v_mov_b32_e32 v52, v2
	v_mov_b32_e32 v53, v2
	v_mov_b32_e32 v54, v2
	v_mov_b32_e32 v55, v2
	v_mov_b32_e32 v56, v2
	v_mov_b32_e32 v57, v2
	v_mov_b32_e32 v58, v2
	v_mov_b32_e32 v59, v2
	v_mov_b32_e32 v60, v2
	v_mov_b32_e32 v61, v2
	v_mov_b32_e32 v62, v2
	v_mov_b32_e32 v63, v2
	v_mov_b32_e32 v64, v2
	v_mov_b32_e32 v65, v2
	v_mov_b32_e32 v66, v2
	v_mov_b32_e32 v67, v2
	v_mov_b32_e32 v68, v2
	v_mov_b32_e32 v69, v2
	v_mov_b32_e32 v70, v2
	v_mov_b32_e32 v71, v2
	v_mov_b32_e32 v72, v2
	v_mov_b32_e32 v73, v2
	v_mov_b32_e32 v74, v2
	v_mov_b32_e32 v75, v2
	v_mov_b32_e32 v76, v2
	v_mov_b32_e32 v77, v2
	v_mov_b32_e32 v78, v2
	v_mov_b32_e32 v79, v2
	v_mov_b32_e32 v80, v2
	v_mov_b32_e32 v81, v2
	v_mov_b32_e32 v90, v2
	v_mov_b32_e32 v91, v2
	v_mov_b32_e32 v92, v2
	v_mov_b32_e32 v93, v2
	v_mov_b32_e32 v94, v2
	v_mov_b32_e32 v95, v2
	v_mov_b32_e32 v96, v2
	v_mov_b32_e32 v97, v2
	v_mov_b32_e32 v106, v2
	v_mov_b32_e32 v107, v2
	v_mov_b32_e32 v108, v2
	v_mov_b32_e32 v109, v2
	v_mov_b32_e32 v110, v2
	v_mov_b32_e32 v111, v2
	v_mov_b32_e32 v112, v2
	v_mov_b32_e32 v113, v2
	v_mov_b32_e32 v82, v2
	v_mov_b32_e32 v83, v2
	v_mov_b32_e32 v84, v2
	v_mov_b32_e32 v85, v2
	v_mov_b32_e32 v86, v2
	v_mov_b32_e32 v87, v2
	v_mov_b32_e32 v88, v2
	v_mov_b32_e32 v89, v2
	v_mov_b32_e32 v98, v2
	v_mov_b32_e32 v99, v2
	v_mov_b32_e32 v100, v2
	v_mov_b32_e32 v101, v2
	v_mov_b32_e32 v102, v2
	v_mov_b32_e32 v103, v2
	v_mov_b32_e32 v104, v2
	v_mov_b32_e32 v105, v2
	v_mov_b32_e32 v114, v2
	v_mov_b32_e32 v115, v2
	v_mov_b32_e32 v116, v2
	v_mov_b32_e32 v117, v2
	v_mov_b32_e32 v118, v2
	v_mov_b32_e32 v119, v2
	v_mov_b32_e32 v120, v2
	v_mov_b32_e32 v121, v2
	v_mov_b32_e32 v122, v2
	v_mov_b32_e32 v123, v2
	v_mov_b32_e32 v124, v2
	v_mov_b32_e32 v125, v2
	v_mov_b32_e32 v126, v2
	v_mov_b32_e32 v127, v2
	v_mov_b32_e32 v128, v2
	v_mov_b32_e32 v129, v2
